# hrows: hoist the 9 serialized norm-weight/scale/shift loads per row to the loop top with counted vmcnt
# baseline (speedup 1.0000x reference)
; __device__ __forceinline__ unsigned pk2(float lo, float hi) { const f32x2 v = {lo, hi}; const bf16x2_t b = __builtin_convertvector(v, bf16x2_t); return __builtin_bit_cast(unsigned, b); }
; __device__ __forceinline__ float dot4(f32x4 a) { return (a[0] * a[0] + a[1] * a[1]) + (a[2] * a[2] + a[3] * a[3]); }
; __device__ __forceinline__ void ph_hrows(int tbase) {
;     ...
;     for (int m = gw; m < TG; m += NGW) { const int t = tbase + m, b = t >> 12;
;         const f32x4* xr = (const f32x4*)(x + (size_t)t * 1024) + lane; f32x4 v[4]; float s = 0.f;
; #pragma unroll
;         for (int j = 0; j < 4; ++j) { v[j] = xr[64 * j]; s += dot4(v[j]); }
;         const float rs = rsqrtf(wave_sum(s) * (1.f / 1024.f) + EPS); const float* shift = MOD + b * 6144; const float* scale = shift + 1024;
; #pragma unroll
;         for (int j = 0; j < 4; ++j) { const int c0 = 4 * lane + 256 * j; const f32x4 g = *(const f32x4*)(g_pre_mix + c0), sc = *(const f32x4*)(scale + c0), sh = *(const f32x4*)(shift + c0);
;             const f32x4 hv = v[j] * rs * g * (sc + 1.f) + sh; u32x2 w; w.x = pk2(hv[0], hv[1]); w.y = pk2(hv[2], hv[3]); *(u32x2*)(H + (size_t)m * 1024 + c0) = w; } }
.LBB0_179:
	global_load_dwordx4 v[18:21], v[6:7], off offset:-2048
	global_load_dwordx4 v[22:25], v[6:7], off offset:-1024
	global_load_dwordx4 v[26:29], v[6:7], off offset:1024
	global_load_dwordx4 v[30:33], v[6:7], off
	s_ashr_i32 s5, s4, 12
	s_mul_i32 s12, s5, 0x1800
	s_ashr_i32 s13, s12, 31
	s_lshl_b64 s[12:13], s[12:13], 2
	s_add_u32 s12, s2, s12
	s_addc_u32 s13, s16, s13
	s_add_u32 s14, s12, 0x1000
	global_load_dwordx4 v[34:37], v[2:3], off
	s_addc_u32 s15, s13, 0
	global_load_dwordx4 v[38:41], v0, s[14:15]
	global_load_dwordx4 v[42:45], v0, s[12:13]
	global_load_dwordx4 v[144:147], v[2:3], off offset:1024
	global_load_dwordx4 v[148:151], v14, s[14:15]
	global_load_dwordx4 v[152:155], v0, s[12:13] offset:1024
	global_load_dwordx4 v[156:159], v[2:3], off offset:2048
	global_load_dwordx4 v[160:163], v15, s[14:15]
	global_load_dwordx4 v[164:167], v0, s[12:13] offset:2048
	global_load_dwordx4 v[168:171], v[2:3], off offset:3072
	global_load_dwordx4 v[172:175], v16, s[14:15]
	global_load_dwordx4 v[176:179], v0, s[12:13] offset:3072
	s_add_i32 s4, s4, s6
	v_lshl_add_u64 v[6:7], v[6:7], 0, s[10:11]
	s_cmpk_gt_i32 s4, 0x3fff
	s_waitcnt vmcnt(15)
	v_pk_mul_f32 v[46:47], v[20:21], v[20:21]
	v_pk_mul_f32 v[48:49], v[18:19], v[18:19]
	s_waitcnt vmcnt(14)
	v_pk_mul_f32 v[50:51], v[24:25], v[24:25]
	v_pk_mul_f32 v[52:53], v[22:23], v[22:23]
	v_pk_mov_b32 v[58:59], v[48:49], v[46:47] op_sel:[1,0]
	v_mov_b32_e32 v49, v47
	v_pk_mov_b32 v[46:47], v[52:53], v[50:51] op_sel:[1,0]
	v_mov_b32_e32 v53, v51
	s_waitcnt vmcnt(13)
	v_mul_f32_e32 v57, v27, v27
	s_waitcnt vmcnt(12)
	v_mul_f32_e32 v54, v31, v31
	v_mul_f32_e32 v56, v33, v33
	v_pk_add_f32 v[48:49], v[58:59], v[48:49]
	v_pk_add_f32 v[46:47], v[46:47], v[52:53]
	v_mul_f32_e32 v17, v26, v26
	v_mul_f32_e32 v60, v28, v28
	v_mul_f32_e32 v61, v29, v29
	v_pk_fma_f32 v[50:51], v[30:31], v[30:31], v[54:55] op_sel_hi:[1,1,0]
	v_pk_fma_f32 v[54:55], v[32:33], v[32:33], v[56:57] op_sel_hi:[1,1,0]
	v_pk_add_f32 v[48:49], v[48:49], v[48:49] op_sel:[0,1] op_sel_hi:[1,0]
	v_pk_add_f32 v[46:47], v[46:47], v[46:47] op_sel:[0,1] op_sel_hi:[1,0]
	v_mov_b32_e32 v51, v60
	v_mov_b32_e32 v55, v61
	v_mov_b32_e32 v49, v17
	v_mov_b32_e32 v47, v57
	v_pk_add_f32 v[50:51], v[50:51], v[54:55]
	v_pk_add_f32 v[46:47], v[48:49], v[46:47]
	s_waitcnt vmcnt(10)
	v_pk_add_f32 v[40:41], v[40:41], 1.0 op_sel_hi:[1,0]
	v_pk_add_f32 v[46:47], v[46:47], v[50:51]
	v_pk_add_f32 v[38:39], v[38:39], 1.0 op_sel_hi:[1,0]
	v_add_f32_e32 v17, v46, v47
	ds_bpermute_b32 v46, v8, v17
	s_waitcnt lgkmcnt(0)
	v_add_f32_e32 v17, v17, v46
	ds_bpermute_b32 v46, v9, v17
	s_waitcnt lgkmcnt(0)
	v_add_f32_e32 v17, v17, v46
	ds_bpermute_b32 v46, v10, v17
	s_waitcnt lgkmcnt(0)
	v_add_f32_e32 v17, v17, v46
	ds_bpermute_b32 v46, v11, v17
	s_waitcnt lgkmcnt(0)
	v_add_f32_e32 v17, v17, v46
	ds_bpermute_b32 v46, v12, v17
	s_waitcnt lgkmcnt(0)
	v_add_f32_e32 v17, v17, v46
	ds_bpermute_b32 v46, v13, v17
	s_waitcnt lgkmcnt(0)
	v_add_f32_e32 v17, v17, v46
	v_fmamk_f32 v17, v17, 0x3a800000, v220
	v_mul_f32_e32 v46, 0x4b800000, v17
	v_cmp_gt_f32_e32 vcc, s51, v17
	s_nop 1
	v_cndmask_b32_e32 v17, v17, v46, vcc
	v_rsq_f32_e32 v17, v17
	s_nop 0
	v_mul_f32_e32 v46, 0x45800000, v17
	v_cndmask_b32_e32 v46, v17, v46, vcc
	v_pk_mul_f32 v[20:21], v[20:21], v[46:47] op_sel_hi:[1,0]
	v_pk_mul_f32 v[18:19], v[18:19], v[46:47] op_sel_hi:[1,0]
	v_pk_mul_f32 v[20:21], v[36:37], v[20:21]
	v_pk_mul_f32 v[18:19], v[34:35], v[18:19]
	s_waitcnt vmcnt(9)
	v_pk_fma_f32 v[20:21], v[40:41], v[20:21], v[44:45]
	v_pk_fma_f32 v[18:19], v[38:39], v[18:19], v[42:43]
	v_pk_mul_f32 v[24:25], v[24:25], v[46:47] op_sel_hi:[1,0]
	v_cvt_pk_bf16_f32 v18, v18, v19
	v_cvt_pk_bf16_f32 v19, v20, v21
	global_store_dwordx2 v[4:5], v[18:19], off
	v_pk_mul_f32 v[22:23], v[22:23], v[46:47] op_sel_hi:[1,0]
	v_pk_mul_f32 v[32:33], v[32:33], v[46:47] op_sel_hi:[1,0]
	v_pk_mul_f32 v[30:31], v[30:31], v[46:47] op_sel_hi:[1,0]
	v_pk_mul_f32 v[28:29], v[28:29], v[46:47] op_sel_hi:[1,0]
	v_pk_mul_f32 v[26:27], v[26:27], v[46:47] op_sel_hi:[1,0]
	s_waitcnt vmcnt(9)
	v_pk_mul_f32 v[18:19], v[144:145], v[22:23]
	v_pk_mul_f32 v[20:21], v[146:147], v[24:25]
	s_waitcnt vmcnt(8)
	v_pk_add_f32 v[22:23], v[150:151], 1.0 op_sel_hi:[1,0]
	v_pk_add_f32 v[24:25], v[148:149], 1.0 op_sel_hi:[1,0]
	s_waitcnt vmcnt(7)
	v_pk_fma_f32 v[20:21], v[22:23], v[20:21], v[154:155]
	v_pk_fma_f32 v[18:19], v[24:25], v[18:19], v[152:153]
	s_nop 0
	v_cvt_pk_bf16_f32 v18, v18, v19
	v_cvt_pk_bf16_f32 v19, v20, v21
	global_store_dwordx2 v[4:5], v[18:19], off offset:512
	s_waitcnt vmcnt(7)
	v_pk_mul_f32 v[18:19], v[156:157], v[30:31]
	v_pk_mul_f32 v[20:21], v[158:159], v[32:33]
	s_waitcnt vmcnt(6)
	v_pk_add_f32 v[24:25], v[162:163], 1.0 op_sel_hi:[1,0]
	v_pk_add_f32 v[22:23], v[160:161], 1.0 op_sel_hi:[1,0]
	s_waitcnt vmcnt(5)
	v_pk_fma_f32 v[20:21], v[24:25], v[20:21], v[166:167]
	v_pk_fma_f32 v[18:19], v[22:23], v[18:19], v[164:165]
	s_nop 0
	v_cvt_pk_bf16_f32 v18, v18, v19
	v_cvt_pk_bf16_f32 v19, v20, v21
	global_store_dwordx2 v[4:5], v[18:19], off offset:1024
	s_waitcnt vmcnt(5)
	v_pk_mul_f32 v[18:19], v[168:169], v[26:27]
	v_pk_mul_f32 v[20:21], v[170:171], v[28:29]
	s_waitcnt vmcnt(4)
	v_pk_add_f32 v[24:25], v[174:175], 1.0 op_sel_hi:[1,0]
	v_pk_add_f32 v[22:23], v[172:173], 1.0 op_sel_hi:[1,0]
	s_waitcnt vmcnt(3)
	v_pk_fma_f32 v[20:21], v[24:25], v[20:21], v[178:179]
	v_pk_fma_f32 v[18:19], v[22:23], v[18:19], v[176:177]
	s_nop 0
	v_cvt_pk_bf16_f32 v18, v18, v19
	v_cvt_pk_bf16_f32 v19, v20, v21
	global_store_dwordx2 v[4:5], v[18:19], off offset:1536
	v_lshl_add_u64 v[4:5], v[4:5], 0, s[8:9]
	s_cbranch_scc0 .LBB0_179
